# v105 without the static priority: half-tile stagger of SIMD partners only
# speedup vs baseline: 1.0057x; 1.0046x over previous
.Lmla_fast:
	s_mov_b32 s42, s30
	s_and_b32 s8, s30, 3
	s_mulk_i32 s8, 0x6400
	s_add_i32 s8, s8, 0
	v_add3_u32 v142, s8, v144, v145
	v_add3_u32 v0, s8, v143, v132
	ds_read_b128 v[194:197], v0
	ds_read_b128 v[150:153], v0 offset:32
	ds_read_b128 v[158:161], v0 offset:64
	ds_read_b128 v[162:165], v0 offset:96
	ds_read_b128 v[174:177], v0 offset:128
	ds_read_b128 v[178:181], v0 offset:160
	s_cmp_lt_u32 s5, 0x1000
	s_cbranch_scc1 .Lmla_fast_grpA
	s_bitcmp1_b32 s30, 0
	s_cbranch_scc1 .Lmla_fast_havek_oB
	s_branch .Lmla_fast_havek_eB
